# GEMM K-loops: LDS-DMA issue moved from the load segment into the MFMA segment in all four GEMM loops, vmcnt re-derived
# baseline (speedup 1.0000x reference)
.LBB0_235:
	ds_read_b128 v[128:131], v173
	ds_read_b128 v[132:135], v173 offset:1024
	ds_read_b128 v[152:155], v173 offset:2048
	ds_read_b128 v[178:181], v173 offset:3072
	ds_read_b128 v[184:187], v174
	ds_read_b128 v[188:191], v174 offset:1024
	ds_read_b128 v[192:195], v174 offset:2048
	ds_read_b128 v[196:199], v174 offset:3072
	s_add_u32 s24, s38, 0xfff80080
	s_addc_u32 s25, s39, -1
	s_cmp_eq_u32 s63, 28
	s_cselect_b32 s47, s5, s25
	s_cselect_b32 s46, s6, s24
	s_cselect_b32 s41, s15, s62
	s_cselect_b32 s40, s17, s43
	v_lshl_add_u64 v[244:245], s[38:39], 0, v[144:145]
	s_add_i32 s96, s77, 0xc000
	ds_read_b128 v[200:203], v175
	ds_read_b128 v[204:207], v175 offset:1024
	ds_read_b128 v[208:211], v175 offset:2048
	ds_read_b128 v[212:215], v175 offset:3072
	ds_read_b128 v[216:219], v175 offset:4096
	ds_read_b128 v[220:223], v175 offset:5120
	ds_read_b128 v[224:227], v175 offset:6144
	ds_read_b128 v[228:231], v175 offset:7168
	v_lshl_add_u64 v[232:233], s[38:39], 0, v[146:147]
	s_add_i32 s97, s77, 0xe000
	s_waitcnt vmcnt(6)
	s_waitcnt lgkmcnt(0)
	s_barrier
	s_setprio 1
	s_waitcnt lgkmcnt(0)
	v_mfma_f32_16x16x32_bf16 v[124:127], v[128:131], v[200:203], v[124:127]
	v_mfma_f32_16x16x32_bf16 v[120:123], v[152:155], v[200:203], v[120:123]
	s_mov_b32 m0, s96
	v_mfma_f32_16x16x32_bf16 v[116:119], v[128:131], v[208:211], v[116:119]
	global_load_lds_dwordx4 v[244:245], off
	v_mfma_f32_16x16x32_bf16 v[112:115], v[152:155], v[208:211], v[112:115]
	v_mfma_f32_16x16x32_bf16 v[108:111], v[128:131], v[216:219], v[108:111]
	v_mfma_f32_16x16x32_bf16 v[104:107], v[152:155], v[216:219], v[104:107]
	s_mov_b32 m0, s97
	v_mfma_f32_16x16x32_bf16 v[100:103], v[128:131], v[224:227], v[100:103]
	global_load_lds_dwordx4 v[232:233], off
	v_mfma_f32_16x16x32_bf16 v[96:99], v[152:155], v[224:227], v[96:99]
	v_mfma_f32_16x16x32_bf16 v[124:127], v[132:135], v[204:207], v[124:127]
	v_mfma_f32_16x16x32_bf16 v[120:123], v[178:181], v[204:207], v[120:123]
	v_mfma_f32_16x16x32_bf16 v[116:119], v[132:135], v[212:215], v[116:119]
	v_mfma_f32_16x16x32_bf16 v[112:115], v[178:181], v[212:215], v[112:115]
	v_mfma_f32_16x16x32_bf16 v[108:111], v[132:135], v[220:223], v[108:111]
	v_mfma_f32_16x16x32_bf16 v[104:107], v[178:181], v[220:223], v[104:107]
	v_mfma_f32_16x16x32_bf16 v[100:103], v[132:135], v[228:231], v[100:103]
	v_mfma_f32_16x16x32_bf16 v[96:99], v[178:181], v[228:231], v[96:99]
	s_setprio 0
	s_setprio 1
	v_mfma_f32_16x16x32_bf16 v[60:63], v[184:187], v[200:203], v[60:63]
	v_mfma_f32_16x16x32_bf16 v[56:59], v[192:195], v[200:203], v[56:59]
	v_mfma_f32_16x16x32_bf16 v[52:55], v[184:187], v[208:211], v[52:55]
	v_mfma_f32_16x16x32_bf16 v[48:51], v[192:195], v[208:211], v[48:51]
	v_mfma_f32_16x16x32_bf16 v[44:47], v[184:187], v[216:219], v[44:47]
	v_mfma_f32_16x16x32_bf16 v[40:43], v[192:195], v[216:219], v[40:43]
	v_mfma_f32_16x16x32_bf16 v[36:39], v[184:187], v[224:227], v[36:39]
	v_mfma_f32_16x16x32_bf16 v[32:35], v[192:195], v[224:227], v[32:35]
	v_mfma_f32_16x16x32_bf16 v[60:63], v[188:191], v[204:207], v[60:63]
	v_mfma_f32_16x16x32_bf16 v[56:59], v[196:199], v[204:207], v[56:59]
	v_mfma_f32_16x16x32_bf16 v[52:55], v[188:191], v[212:215], v[52:55]
	v_mfma_f32_16x16x32_bf16 v[48:51], v[196:199], v[212:215], v[48:51]
	v_mfma_f32_16x16x32_bf16 v[44:47], v[188:191], v[220:223], v[44:47]
	v_mfma_f32_16x16x32_bf16 v[40:43], v[196:199], v[220:223], v[40:43]
	v_mfma_f32_16x16x32_bf16 v[36:39], v[188:191], v[228:231], v[36:39]
	v_mfma_f32_16x16x32_bf16 v[32:35], v[196:199], v[228:231], v[32:35]
	s_setprio 0
	s_barrier
	s_add_i32 s24, s87, s76
	v_lshl_add_u64 v[232:233], s[40:41], 0, v[138:139]
	s_mov_b32 s96, s24
	ds_read_b128 v[200:203], v175 offset:16384
	ds_read_b128 v[204:207], v175 offset:17408
	ds_read_b128 v[208:211], v175 offset:18432
	ds_read_b128 v[212:215], v175 offset:19456
	ds_read_b128 v[216:219], v175 offset:20480
	ds_read_b128 v[220:223], v175 offset:21504
	ds_read_b128 v[224:227], v175 offset:22528
	ds_read_b128 v[228:231], v175 offset:23552
	s_add_i32 s97, s24, 0x2000
	s_add_u32 s24, s40, 0x80000
	v_lshl_add_u64 v[234:235], s[40:41], 0, v[142:143]
	s_addc_u32 s25, s41, 0
	s_add_i32 s26, s88, s76
	v_lshl_add_u64 v[244:245], s[24:25], 0, v[138:139]
	s_mov_b32 s98, s26
	v_lshl_add_u64 v[238:239], s[46:47], 0, v[140:141]
	v_lshl_add_u64 v[246:247], s[24:25], 0, v[142:143]
	s_add_i32 s99, s26, 0x2000
	v_lshl_add_u64 v[236:237], s[46:47], 0, v[136:137]
	s_mov_b32 s100, s77
	s_mov_b32 s101, s78
	s_waitcnt vmcnt(2)
	s_waitcnt lgkmcnt(0)
	s_barrier
	s_setprio 1
	s_waitcnt lgkmcnt(0)
	v_mfma_f32_16x16x32_bf16 v[92:95], v[128:131], v[200:203], v[92:95]
	v_mfma_f32_16x16x32_bf16 v[88:91], v[152:155], v[200:203], v[88:91]
	s_mov_b32 m0, s96
	v_mfma_f32_16x16x32_bf16 v[84:87], v[128:131], v[208:211], v[84:87]
	global_load_lds_dwordx4 v[232:233], off
	v_mfma_f32_16x16x32_bf16 v[80:83], v[152:155], v[208:211], v[80:83]
	v_mfma_f32_16x16x32_bf16 v[76:79], v[128:131], v[216:219], v[76:79]
	v_mfma_f32_16x16x32_bf16 v[72:75], v[152:155], v[216:219], v[72:75]
	s_mov_b32 m0, s97
	v_mfma_f32_16x16x32_bf16 v[68:71], v[128:131], v[224:227], v[68:71]
	global_load_lds_dwordx4 v[234:235], off
	v_mfma_f32_16x16x32_bf16 v[64:67], v[152:155], v[224:227], v[64:67]
	v_mfma_f32_16x16x32_bf16 v[92:95], v[132:135], v[204:207], v[92:95]
	v_mfma_f32_16x16x32_bf16 v[88:91], v[178:181], v[204:207], v[88:91]
	s_mov_b32 m0, s98
	v_mfma_f32_16x16x32_bf16 v[84:87], v[132:135], v[212:215], v[84:87]
	global_load_lds_dwordx4 v[244:245], off
	v_mfma_f32_16x16x32_bf16 v[80:83], v[178:181], v[212:215], v[80:83]
	v_mfma_f32_16x16x32_bf16 v[76:79], v[132:135], v[220:223], v[76:79]
	v_mfma_f32_16x16x32_bf16 v[72:75], v[178:181], v[220:223], v[72:75]
	s_mov_b32 m0, s99
	v_mfma_f32_16x16x32_bf16 v[68:71], v[132:135], v[228:231], v[68:71]
	global_load_lds_dwordx4 v[246:247], off
	v_mfma_f32_16x16x32_bf16 v[64:67], v[178:181], v[228:231], v[64:67]
	s_setprio 0
	s_setprio 1
	v_mfma_f32_16x16x32_bf16 v[28:31], v[184:187], v[200:203], v[28:31]
	v_mfma_f32_16x16x32_bf16 v[24:27], v[192:195], v[200:203], v[24:27]
	s_mov_b32 m0, s100
	v_mfma_f32_16x16x32_bf16 v[20:23], v[184:187], v[208:211], v[20:23]
	global_load_lds_dwordx4 v[236:237], off
	v_mfma_f32_16x16x32_bf16 v[16:19], v[192:195], v[208:211], v[16:19]
	v_mfma_f32_16x16x32_bf16 v[12:15], v[184:187], v[216:219], v[12:15]
	v_mfma_f32_16x16x32_bf16 v[8:11], v[192:195], v[216:219], v[8:11]
	s_mov_b32 m0, s101
	v_mfma_f32_16x16x32_bf16 v[4:7], v[184:187], v[224:227], v[4:7]
	global_load_lds_dwordx4 v[238:239], off
	v_mfma_f32_16x16x32_bf16 v[0:3], v[192:195], v[224:227], v[0:3]
	v_mfma_f32_16x16x32_bf16 v[28:31], v[188:191], v[204:207], v[28:31]
	v_mfma_f32_16x16x32_bf16 v[24:27], v[196:199], v[204:207], v[24:27]
	v_mfma_f32_16x16x32_bf16 v[20:23], v[188:191], v[212:215], v[20:23]
	v_mfma_f32_16x16x32_bf16 v[16:19], v[196:199], v[212:215], v[16:19]
	v_mfma_f32_16x16x32_bf16 v[12:15], v[188:191], v[220:223], v[12:15]
	v_mfma_f32_16x16x32_bf16 v[8:11], v[196:199], v[220:223], v[8:11]
	v_mfma_f32_16x16x32_bf16 v[4:7], v[188:191], v[228:231], v[4:7]
	v_mfma_f32_16x16x32_bf16 v[0:3], v[196:199], v[228:231], v[0:3]
	s_setprio 0
	s_barrier
	s_add_i32 s26, 0, 0x18000
	v_add_u32_e32 v177, s26, v166
	s_add_i32 s27, 0, 0x1c000
	ds_read_b128 v[128:131], v177
	ds_read_b128 v[132:135], v177 offset:1024
	ds_read_b128 v[152:155], v177 offset:2048
	ds_read_b128 v[178:181], v177 offset:3072
	v_add_u32_e32 v177, s27, v166
	ds_read_b128 v[184:187], v177
	ds_read_b128 v[188:191], v177 offset:1024
	ds_read_b128 v[192:195], v177 offset:2048
	ds_read_b128 v[196:199], v177 offset:3072
	s_add_u32 s24, s46, 0x80000
	s_addc_u32 s25, s47, 0
	s_mov_b32 s96, s79
	v_lshl_add_u64 v[244:245], s[24:25], 0, v[136:137]
	ds_read_b128 v[200:203], v175 offset:32768
	ds_read_b128 v[204:207], v175 offset:33792
	ds_read_b128 v[208:211], v175 offset:34816
	ds_read_b128 v[212:215], v175 offset:35840
	ds_read_b128 v[216:219], v175 offset:36864
	ds_read_b128 v[220:223], v175 offset:37888
	ds_read_b128 v[224:227], v175 offset:38912
	ds_read_b128 v[228:231], v175 offset:39936
	v_lshl_add_u64 v[240:241], s[24:25], 0, v[140:141]
	s_mov_b32 s97, s80
	s_waitcnt vmcnt(6)
	s_waitcnt lgkmcnt(0)
	s_barrier
	s_setprio 1
	s_waitcnt lgkmcnt(0)
	v_mfma_f32_16x16x32_bf16 v[124:127], v[128:131], v[200:203], v[124:127]
	v_mfma_f32_16x16x32_bf16 v[120:123], v[152:155], v[200:203], v[120:123]
	s_mov_b32 m0, s96
	v_mfma_f32_16x16x32_bf16 v[116:119], v[128:131], v[208:211], v[116:119]
	global_load_lds_dwordx4 v[244:245], off
	v_mfma_f32_16x16x32_bf16 v[112:115], v[152:155], v[208:211], v[112:115]
	v_mfma_f32_16x16x32_bf16 v[108:111], v[128:131], v[216:219], v[108:111]
	v_mfma_f32_16x16x32_bf16 v[104:107], v[152:155], v[216:219], v[104:107]
	s_mov_b32 m0, s97
	v_mfma_f32_16x16x32_bf16 v[100:103], v[128:131], v[224:227], v[100:103]
	global_load_lds_dwordx4 v[240:241], off
	v_mfma_f32_16x16x32_bf16 v[96:99], v[152:155], v[224:227], v[96:99]
	v_mfma_f32_16x16x32_bf16 v[124:127], v[132:135], v[204:207], v[124:127]
	v_mfma_f32_16x16x32_bf16 v[120:123], v[178:181], v[204:207], v[120:123]
	v_mfma_f32_16x16x32_bf16 v[116:119], v[132:135], v[212:215], v[116:119]
	v_mfma_f32_16x16x32_bf16 v[112:115], v[178:181], v[212:215], v[112:115]
	v_mfma_f32_16x16x32_bf16 v[108:111], v[132:135], v[220:223], v[108:111]
	v_mfma_f32_16x16x32_bf16 v[104:107], v[178:181], v[220:223], v[104:107]
	v_mfma_f32_16x16x32_bf16 v[100:103], v[132:135], v[228:231], v[100:103]
	v_mfma_f32_16x16x32_bf16 v[96:99], v[178:181], v[228:231], v[96:99]
	s_setprio 0
	s_setprio 1
	v_mfma_f32_16x16x32_bf16 v[60:63], v[184:187], v[200:203], v[60:63]
	v_mfma_f32_16x16x32_bf16 v[56:59], v[192:195], v[200:203], v[56:59]
	v_mfma_f32_16x16x32_bf16 v[52:55], v[184:187], v[208:211], v[52:55]
	v_mfma_f32_16x16x32_bf16 v[48:51], v[192:195], v[208:211], v[48:51]
	v_mfma_f32_16x16x32_bf16 v[44:47], v[184:187], v[216:219], v[44:47]
	v_mfma_f32_16x16x32_bf16 v[40:43], v[192:195], v[216:219], v[40:43]
	v_mfma_f32_16x16x32_bf16 v[36:39], v[184:187], v[224:227], v[36:39]
	v_mfma_f32_16x16x32_bf16 v[32:35], v[192:195], v[224:227], v[32:35]
	v_mfma_f32_16x16x32_bf16 v[60:63], v[188:191], v[204:207], v[60:63]
	v_mfma_f32_16x16x32_bf16 v[56:59], v[196:199], v[204:207], v[56:59]
	v_mfma_f32_16x16x32_bf16 v[52:55], v[188:191], v[212:215], v[52:55]
	v_mfma_f32_16x16x32_bf16 v[48:51], v[196:199], v[212:215], v[48:51]
	v_mfma_f32_16x16x32_bf16 v[44:47], v[188:191], v[220:223], v[44:47]
	v_mfma_f32_16x16x32_bf16 v[40:43], v[196:199], v[220:223], v[40:43]
	v_mfma_f32_16x16x32_bf16 v[36:39], v[188:191], v[228:231], v[36:39]
	v_mfma_f32_16x16x32_bf16 v[32:35], v[196:199], v[228:231], v[32:35]
	s_setprio 0
	s_barrier
	s_add_i32 s24, s26, s76
	v_lshl_add_u64 v[244:245], v[232:233], 0, s[10:11]
	s_mov_b32 s96, s24
	ds_read_b128 v[200:203], v175 offset:49152
	ds_read_b128 v[204:207], v175 offset:50176
	ds_read_b128 v[208:211], v175 offset:51200
	ds_read_b128 v[212:215], v175 offset:52224
	ds_read_b128 v[216:219], v175 offset:53248
	ds_read_b128 v[220:223], v175 offset:54272
	ds_read_b128 v[224:227], v175 offset:55296
	ds_read_b128 v[228:231], v175 offset:56320
	s_add_i32 s97, s24, 0x2000
	s_add_u32 s24, s40, 0x80080
	v_lshl_add_u64 v[246:247], v[234:235], 0, s[10:11]
	s_addc_u32 s25, s41, 0
	s_add_i32 s26, s27, s76
	v_lshl_add_u64 v[248:249], s[24:25], 0, v[138:139]
	s_mov_b32 s98, s26
	v_lshl_add_u64 v[250:251], s[24:25], 0, v[142:143]
	s_add_i32 s99, s26, 0x2000
	v_lshl_add_u64 v[252:253], v[236:237], 0, s[10:11]
	s_mov_b32 s100, s81
	v_lshl_add_u64 v[232:233], v[238:239], 0, s[10:11]
	s_mov_b32 s101, s82
	s_waitcnt vmcnt(2)
	s_waitcnt lgkmcnt(0)
	s_barrier
	s_setprio 1
	s_waitcnt lgkmcnt(0)
	v_mfma_f32_16x16x32_bf16 v[92:95], v[128:131], v[200:203], v[92:95]
	v_mfma_f32_16x16x32_bf16 v[88:91], v[152:155], v[200:203], v[88:91]
	s_mov_b32 m0, s96
	v_mfma_f32_16x16x32_bf16 v[84:87], v[128:131], v[208:211], v[84:87]
	global_load_lds_dwordx4 v[244:245], off
	v_mfma_f32_16x16x32_bf16 v[80:83], v[152:155], v[208:211], v[80:83]
	v_mfma_f32_16x16x32_bf16 v[76:79], v[128:131], v[216:219], v[76:79]
	v_mfma_f32_16x16x32_bf16 v[72:75], v[152:155], v[216:219], v[72:75]
	s_mov_b32 m0, s97
	v_mfma_f32_16x16x32_bf16 v[68:71], v[128:131], v[224:227], v[68:71]
	global_load_lds_dwordx4 v[246:247], off
	v_mfma_f32_16x16x32_bf16 v[64:67], v[152:155], v[224:227], v[64:67]
	v_mfma_f32_16x16x32_bf16 v[92:95], v[132:135], v[204:207], v[92:95]
	v_mfma_f32_16x16x32_bf16 v[88:91], v[178:181], v[204:207], v[88:91]
	s_mov_b32 m0, s98
	v_mfma_f32_16x16x32_bf16 v[84:87], v[132:135], v[212:215], v[84:87]
	global_load_lds_dwordx4 v[248:249], off
	v_mfma_f32_16x16x32_bf16 v[80:83], v[178:181], v[212:215], v[80:83]
	v_mfma_f32_16x16x32_bf16 v[76:79], v[132:135], v[220:223], v[76:79]
	v_mfma_f32_16x16x32_bf16 v[72:75], v[178:181], v[220:223], v[72:75]
	s_mov_b32 m0, s99
	v_mfma_f32_16x16x32_bf16 v[68:71], v[132:135], v[228:231], v[68:71]
	global_load_lds_dwordx4 v[250:251], off
	v_mfma_f32_16x16x32_bf16 v[64:67], v[178:181], v[228:231], v[64:67]
	s_setprio 0
	s_setprio 1
	v_mfma_f32_16x16x32_bf16 v[28:31], v[184:187], v[200:203], v[28:31]
	v_mfma_f32_16x16x32_bf16 v[24:27], v[192:195], v[200:203], v[24:27]
	s_mov_b32 m0, s100
	v_mfma_f32_16x16x32_bf16 v[20:23], v[184:187], v[208:211], v[20:23]
	global_load_lds_dwordx4 v[252:253], off
	v_mfma_f32_16x16x32_bf16 v[16:19], v[192:195], v[208:211], v[16:19]
	v_mfma_f32_16x16x32_bf16 v[12:15], v[184:187], v[216:219], v[12:15]
	v_mfma_f32_16x16x32_bf16 v[8:11], v[192:195], v[216:219], v[8:11]
	s_mov_b32 m0, s101
	v_mfma_f32_16x16x32_bf16 v[4:7], v[184:187], v[224:227], v[4:7]
	global_load_lds_dwordx4 v[232:233], off
	v_mfma_f32_16x16x32_bf16 v[0:3], v[192:195], v[224:227], v[0:3]
	v_mfma_f32_16x16x32_bf16 v[28:31], v[188:191], v[204:207], v[28:31]
	v_mfma_f32_16x16x32_bf16 v[24:27], v[196:199], v[204:207], v[24:27]
	v_mfma_f32_16x16x32_bf16 v[20:23], v[188:191], v[212:215], v[20:23]
	v_mfma_f32_16x16x32_bf16 v[16:19], v[196:199], v[212:215], v[16:19]
	v_mfma_f32_16x16x32_bf16 v[12:15], v[188:191], v[220:223], v[12:15]
	v_mfma_f32_16x16x32_bf16 v[8:11], v[196:199], v[220:223], v[8:11]
	v_mfma_f32_16x16x32_bf16 v[4:7], v[188:191], v[228:231], v[4:7]
	v_mfma_f32_16x16x32_bf16 v[0:3], v[196:199], v[228:231], v[0:3]
	s_setprio 0
	s_barrier
	s_add_i32 s63, s63, 2
	s_add_u32 s38, s38, 0x100
	s_addc_u32 s39, s39, 0
	s_add_u32 s43, s43, 0x100
	s_addc_u32 s62, s62, 0
	s_cmp_gt_u32 s63, 29
	s_cbranch_scc0 .LBB0_235
	s_and_b64 vcc, exec, s[12:13]
	s_cbranch_vccz .LBB0_238
	s_barrier

.LBB0_349:
	ds_read_b128 v[16:19], v186
	ds_read_b128 v[20:23], v186 offset:1024
	ds_read_b128 v[24:27], v186 offset:2048
	ds_read_b128 v[28:31], v186 offset:3072
	ds_read_b128 v[0:3], v187
	ds_read_b128 v[4:7], v187 offset:1024
	ds_read_b128 v[8:11], v187 offset:2048
	ds_read_b128 v[12:15], v187 offset:3072
	s_add_u32 s24, s62, 0xfffc0080
	s_addc_u32 s25, s63, -1
	s_cmp_eq_u32 s71, 12
	s_cselect_b32 s69, s1, s25
	s_cselect_b32 s68, s8, s24
	s_cselect_b32 s67, s23, s70
	s_cselect_b32 s66, s39, s65
	v_lshl_add_u64 v[244:245], s[62:63], 0, v[170:171]
	s_add_i32 s96, s81, 0xc000
	ds_read_b128 v[174:177], v188
	ds_read_b128 v[178:181], v188 offset:1024
	ds_read_b128 v[190:193], v188 offset:2048
	ds_read_b128 v[194:197], v188 offset:3072
	ds_read_b128 v[198:201], v188 offset:4096
	ds_read_b128 v[202:205], v188 offset:5120
	ds_read_b128 v[206:209], v188 offset:6144
	ds_read_b128 v[210:213], v188 offset:7168
	v_lshl_add_u64 v[214:215], s[62:63], 0, v[172:173]
	s_add_i32 s97, s81, 0xe000
	s_waitcnt vmcnt(6)
	s_waitcnt lgkmcnt(0)
	s_barrier
	s_setprio 1
	s_waitcnt lgkmcnt(0)
	s_nop 1
	v_mfma_scale_f32_16x16x128_f8f6f4 v[156:159], v[16:23], v[174:181], v[156:159], v189, v189 op_sel_hi:[0,0,0]
	s_mov_b32 m0, s96
	s_nop 1
	v_mfma_scale_f32_16x16x128_f8f6f4 v[152:155], v[24:31], v[174:181], v[152:155], v189, v189 op_sel_hi:[0,0,0]
	global_load_lds_dwordx4 v[244:245], off
	s_nop 1
	v_mfma_scale_f32_16x16x128_f8f6f4 v[148:151], v[16:23], v[190:197], v[148:151], v189, v189 op_sel_hi:[0,0,0]
	s_mov_b32 m0, s97
	s_nop 1
	v_mfma_scale_f32_16x16x128_f8f6f4 v[144:147], v[24:31], v[190:197], v[144:147], v189, v189 op_sel_hi:[0,0,0]
	global_load_lds_dwordx4 v[214:215], off
	s_nop 1
	v_mfma_scale_f32_16x16x128_f8f6f4 v[140:143], v[16:23], v[198:205], v[140:143], v189, v189 op_sel_hi:[0,0,0]
	s_nop 1
	v_mfma_scale_f32_16x16x128_f8f6f4 v[136:139], v[24:31], v[198:205], v[136:139], v189, v189 op_sel_hi:[0,0,0]
	s_nop 1
	v_mfma_scale_f32_16x16x128_f8f6f4 v[132:135], v[16:23], v[206:213], v[132:135], v189, v189 op_sel_hi:[0,0,0]
	s_nop 1
	v_mfma_scale_f32_16x16x128_f8f6f4 v[128:131], v[24:31], v[206:213], v[128:131], v189, v189 op_sel_hi:[0,0,0]
	s_setprio 0
	s_setprio 1
	s_nop 1
	v_mfma_scale_f32_16x16x128_f8f6f4 v[92:95], v[0:7], v[174:181], v[92:95], v189, v189 op_sel_hi:[0,0,0]
	s_nop 1
	v_mfma_scale_f32_16x16x128_f8f6f4 v[88:91], v[8:15], v[174:181], v[88:91], v189, v189 op_sel_hi:[0,0,0]
	s_nop 1
	v_mfma_scale_f32_16x16x128_f8f6f4 v[84:87], v[0:7], v[190:197], v[84:87], v189, v189 op_sel_hi:[0,0,0]
	s_nop 1
	v_mfma_scale_f32_16x16x128_f8f6f4 v[80:83], v[8:15], v[190:197], v[80:83], v189, v189 op_sel_hi:[0,0,0]
	s_nop 1
	v_mfma_scale_f32_16x16x128_f8f6f4 v[76:79], v[0:7], v[198:205], v[76:79], v189, v189 op_sel_hi:[0,0,0]
	s_nop 1
	v_mfma_scale_f32_16x16x128_f8f6f4 v[72:75], v[8:15], v[198:205], v[72:75], v189, v189 op_sel_hi:[0,0,0]
	s_nop 1
	v_mfma_scale_f32_16x16x128_f8f6f4 v[68:71], v[0:7], v[206:213], v[68:71], v189, v189 op_sel_hi:[0,0,0]
	s_nop 1
	v_mfma_scale_f32_16x16x128_f8f6f4 v[64:67], v[8:15], v[206:213], v[64:67], v189, v189 op_sel_hi:[0,0,0]
	s_setprio 0
	s_barrier
	s_add_i32 s24, s90, s80
	v_lshl_add_u64 v[174:175], s[66:67], 0, v[162:163]
	s_mov_b32 s96, s24
	ds_read_b128 v[190:193], v188 offset:16384
	ds_read_b128 v[194:197], v188 offset:17408
	ds_read_b128 v[198:201], v188 offset:18432
	ds_read_b128 v[202:205], v188 offset:19456
	ds_read_b128 v[206:209], v188 offset:20480
	ds_read_b128 v[210:213], v188 offset:21504
	ds_read_b128 v[214:217], v188 offset:22528
	ds_read_b128 v[218:221], v188 offset:23552
	s_add_i32 s97, s24, 0x2000
	s_add_u32 s24, s66, 0x40000
	v_lshl_add_u64 v[176:177], s[66:67], 0, v[166:167]
	s_addc_u32 s25, s67, 0
	s_add_i32 s26, s91, s80
	v_lshl_add_u64 v[244:245], s[24:25], 0, v[162:163]
	s_mov_b32 s98, s26
	v_lshl_add_u64 v[180:181], s[68:69], 0, v[164:165]
	v_lshl_add_u64 v[246:247], s[24:25], 0, v[166:167]
	s_add_i32 s99, s26, 0x2000
	v_lshl_add_u64 v[178:179], s[68:69], 0, v[160:161]
	s_mov_b32 s100, s81
	s_mov_b32 s101, s82
	s_waitcnt vmcnt(2)
	s_waitcnt lgkmcnt(0)
	s_barrier
	s_setprio 1
	s_waitcnt lgkmcnt(0)
	s_nop 1
	v_mfma_scale_f32_16x16x128_f8f6f4 v[124:127], v[16:23], v[190:197], v[124:127], v189, v189 op_sel_hi:[0,0,0]
	s_mov_b32 m0, s96
	s_nop 1
	v_mfma_scale_f32_16x16x128_f8f6f4 v[120:123], v[24:31], v[190:197], v[120:123], v189, v189 op_sel_hi:[0,0,0]
	global_load_lds_dwordx4 v[174:175], off
	s_nop 1
	v_mfma_scale_f32_16x16x128_f8f6f4 v[116:119], v[16:23], v[198:205], v[116:119], v189, v189 op_sel_hi:[0,0,0]
	s_mov_b32 m0, s97
	s_nop 1
	v_mfma_scale_f32_16x16x128_f8f6f4 v[112:115], v[24:31], v[198:205], v[112:115], v189, v189 op_sel_hi:[0,0,0]
	global_load_lds_dwordx4 v[176:177], off
	s_nop 1
	v_mfma_scale_f32_16x16x128_f8f6f4 v[108:111], v[16:23], v[206:213], v[108:111], v189, v189 op_sel_hi:[0,0,0]
	s_mov_b32 m0, s98
	s_nop 1
	v_mfma_scale_f32_16x16x128_f8f6f4 v[104:107], v[24:31], v[206:213], v[104:107], v189, v189 op_sel_hi:[0,0,0]
	global_load_lds_dwordx4 v[244:245], off
	s_nop 1
	v_mfma_scale_f32_16x16x128_f8f6f4 v[100:103], v[16:23], v[214:221], v[100:103], v189, v189 op_sel_hi:[0,0,0]
	s_mov_b32 m0, s99
	s_nop 1
	v_mfma_scale_f32_16x16x128_f8f6f4 v[96:99], v[24:31], v[214:221], v[96:99], v189, v189 op_sel_hi:[0,0,0]
	global_load_lds_dwordx4 v[246:247], off
	s_setprio 0
	s_setprio 1
	s_nop 1
	v_mfma_scale_f32_16x16x128_f8f6f4 v[60:63], v[0:7], v[190:197], v[60:63], v189, v189 op_sel_hi:[0,0,0]
	s_mov_b32 m0, s100
	s_nop 1
	v_mfma_scale_f32_16x16x128_f8f6f4 v[56:59], v[8:15], v[190:197], v[56:59], v189, v189 op_sel_hi:[0,0,0]
	global_load_lds_dwordx4 v[178:179], off
	s_nop 1
	v_mfma_scale_f32_16x16x128_f8f6f4 v[52:55], v[0:7], v[198:205], v[52:55], v189, v189 op_sel_hi:[0,0,0]
	s_mov_b32 m0, s101
	s_nop 1
	v_mfma_scale_f32_16x16x128_f8f6f4 v[48:51], v[8:15], v[198:205], v[48:51], v189, v189 op_sel_hi:[0,0,0]
	global_load_lds_dwordx4 v[180:181], off
	s_nop 1
	v_mfma_scale_f32_16x16x128_f8f6f4 v[44:47], v[0:7], v[206:213], v[44:47], v189, v189 op_sel_hi:[0,0,0]
	s_nop 1
	v_mfma_scale_f32_16x16x128_f8f6f4 v[40:43], v[8:15], v[206:213], v[40:43], v189, v189 op_sel_hi:[0,0,0]
	s_nop 1
	v_mfma_scale_f32_16x16x128_f8f6f4 v[36:39], v[0:7], v[214:221], v[36:39], v189, v189 op_sel_hi:[0,0,0]
	s_nop 1
	v_mfma_scale_f32_16x16x128_f8f6f4 v[32:35], v[8:15], v[214:221], v[32:35], v189, v189 op_sel_hi:[0,0,0]
	s_setprio 0
	s_barrier
	s_add_i32 s26, 0, 0x18000
	s_add_i32 s27, 0, 0x1c000
	v_add_u32_e32 v12, s26, v184
	v_add_u32_e32 v28, s27, v184
	ds_read_b128 v[0:3], v12
	ds_read_b128 v[4:7], v12 offset:1024
	ds_read_b128 v[8:11], v12 offset:2048
	ds_read_b128 v[12:15], v12 offset:3072
	ds_read_b128 v[16:19], v28
	ds_read_b128 v[20:23], v28 offset:1024
	ds_read_b128 v[24:27], v28 offset:2048
	ds_read_b128 v[28:31], v28 offset:3072
	s_add_u32 s24, s68, 0x40000
	s_addc_u32 s25, s69, 0
	s_mov_b32 s96, s83
	v_lshl_add_u64 v[244:245], s[24:25], 0, v[160:161]
	ds_read_b128 v[190:193], v188 offset:32768
	ds_read_b128 v[194:197], v188 offset:33792
	ds_read_b128 v[198:201], v188 offset:34816
	ds_read_b128 v[202:205], v188 offset:35840
	ds_read_b128 v[206:209], v188 offset:36864
	ds_read_b128 v[210:213], v188 offset:37888
	ds_read_b128 v[214:217], v188 offset:38912
	ds_read_b128 v[218:221], v188 offset:39936
	v_lshl_add_u64 v[222:223], s[24:25], 0, v[164:165]
	s_mov_b32 s97, s84
	s_waitcnt vmcnt(6)
	s_waitcnt lgkmcnt(0)
	s_barrier
	s_setprio 1
	s_waitcnt lgkmcnt(0)
	s_nop 1
	v_mfma_scale_f32_16x16x128_f8f6f4 v[156:159], v[0:7], v[190:197], v[156:159], v189, v189 op_sel_hi:[0,0,0]
	s_mov_b32 m0, s96
	s_nop 1
	v_mfma_scale_f32_16x16x128_f8f6f4 v[152:155], v[8:15], v[190:197], v[152:155], v189, v189 op_sel_hi:[0,0,0]
	global_load_lds_dwordx4 v[244:245], off
	s_nop 1
	v_mfma_scale_f32_16x16x128_f8f6f4 v[148:151], v[0:7], v[198:205], v[148:151], v189, v189 op_sel_hi:[0,0,0]
	s_mov_b32 m0, s97
	s_nop 1
	v_mfma_scale_f32_16x16x128_f8f6f4 v[144:147], v[8:15], v[198:205], v[144:147], v189, v189 op_sel_hi:[0,0,0]
	global_load_lds_dwordx4 v[222:223], off
	s_nop 1
	v_mfma_scale_f32_16x16x128_f8f6f4 v[140:143], v[0:7], v[206:213], v[140:143], v189, v189 op_sel_hi:[0,0,0]
	s_nop 1
	v_mfma_scale_f32_16x16x128_f8f6f4 v[136:139], v[8:15], v[206:213], v[136:139], v189, v189 op_sel_hi:[0,0,0]
	s_nop 1
	v_mfma_scale_f32_16x16x128_f8f6f4 v[132:135], v[0:7], v[214:221], v[132:135], v189, v189 op_sel_hi:[0,0,0]
	s_nop 1
	v_mfma_scale_f32_16x16x128_f8f6f4 v[128:131], v[8:15], v[214:221], v[128:131], v189, v189 op_sel_hi:[0,0,0]
	s_setprio 0
	s_setprio 1
	s_nop 1
	v_mfma_scale_f32_16x16x128_f8f6f4 v[92:95], v[16:23], v[190:197], v[92:95], v189, v189 op_sel_hi:[0,0,0]
	s_nop 1
	v_mfma_scale_f32_16x16x128_f8f6f4 v[88:91], v[24:31], v[190:197], v[88:91], v189, v189 op_sel_hi:[0,0,0]
	s_nop 1
	v_mfma_scale_f32_16x16x128_f8f6f4 v[84:87], v[16:23], v[198:205], v[84:87], v189, v189 op_sel_hi:[0,0,0]
	s_nop 1
	v_mfma_scale_f32_16x16x128_f8f6f4 v[80:83], v[24:31], v[198:205], v[80:83], v189, v189 op_sel_hi:[0,0,0]
	s_nop 1
	v_mfma_scale_f32_16x16x128_f8f6f4 v[76:79], v[16:23], v[206:213], v[76:79], v189, v189 op_sel_hi:[0,0,0]
	s_nop 1
	v_mfma_scale_f32_16x16x128_f8f6f4 v[72:75], v[24:31], v[206:213], v[72:75], v189, v189 op_sel_hi:[0,0,0]
	s_nop 1
	v_mfma_scale_f32_16x16x128_f8f6f4 v[68:71], v[16:23], v[214:221], v[68:71], v189, v189 op_sel_hi:[0,0,0]
	s_nop 1
	v_mfma_scale_f32_16x16x128_f8f6f4 v[64:67], v[24:31], v[214:221], v[64:67], v189, v189 op_sel_hi:[0,0,0]
	s_setprio 0
	s_barrier
	s_add_i32 s24, s26, s80
	v_lshl_add_u64 v[244:245], v[174:175], 0, s[12:13]
	s_mov_b32 s96, s24
	ds_read_b128 v[190:193], v188 offset:49152
	ds_read_b128 v[194:197], v188 offset:50176
	ds_read_b128 v[198:201], v188 offset:51200
	ds_read_b128 v[202:205], v188 offset:52224
	ds_read_b128 v[206:209], v188 offset:53248
	ds_read_b128 v[210:213], v188 offset:54272
	ds_read_b128 v[214:217], v188 offset:55296
	ds_read_b128 v[218:221], v188 offset:56320
	s_add_i32 s97, s24, 0x2000
	s_add_u32 s24, s66, 0x40080
	v_lshl_add_u64 v[246:247], v[176:177], 0, s[12:13]
	s_addc_u32 s25, s67, 0
	s_add_i32 s26, s27, s80
	v_lshl_add_u64 v[248:249], s[24:25], 0, v[162:163]
	s_mov_b32 s98, s26
	v_lshl_add_u64 v[250:251], s[24:25], 0, v[166:167]
	s_add_i32 s99, s26, 0x2000
	v_lshl_add_u64 v[252:253], v[178:179], 0, s[12:13]
	s_mov_b32 s100, s86
	v_lshl_add_u64 v[174:175], v[180:181], 0, s[12:13]
	s_mov_b32 s101, s87
	s_waitcnt vmcnt(2)
	s_waitcnt lgkmcnt(0)
	s_barrier
	s_setprio 1
	s_waitcnt lgkmcnt(0)
	s_nop 1
	v_mfma_scale_f32_16x16x128_f8f6f4 v[124:127], v[0:7], v[190:197], v[124:127], v189, v189 op_sel_hi:[0,0,0]
	s_mov_b32 m0, s96
	s_nop 1
	v_mfma_scale_f32_16x16x128_f8f6f4 v[120:123], v[8:15], v[190:197], v[120:123], v189, v189 op_sel_hi:[0,0,0]
	global_load_lds_dwordx4 v[244:245], off
	s_nop 1
	v_mfma_scale_f32_16x16x128_f8f6f4 v[116:119], v[0:7], v[198:205], v[116:119], v189, v189 op_sel_hi:[0,0,0]
	s_mov_b32 m0, s97
	s_nop 1
	v_mfma_scale_f32_16x16x128_f8f6f4 v[112:115], v[8:15], v[198:205], v[112:115], v189, v189 op_sel_hi:[0,0,0]
	global_load_lds_dwordx4 v[246:247], off
	s_nop 1
	v_mfma_scale_f32_16x16x128_f8f6f4 v[108:111], v[0:7], v[206:213], v[108:111], v189, v189 op_sel_hi:[0,0,0]
	s_mov_b32 m0, s98
	s_nop 1
	v_mfma_scale_f32_16x16x128_f8f6f4 v[104:107], v[8:15], v[206:213], v[104:107], v189, v189 op_sel_hi:[0,0,0]
	global_load_lds_dwordx4 v[248:249], off
	s_nop 1
	v_mfma_scale_f32_16x16x128_f8f6f4 v[100:103], v[0:7], v[214:221], v[100:103], v189, v189 op_sel_hi:[0,0,0]
	s_mov_b32 m0, s99
	s_nop 1
	v_mfma_scale_f32_16x16x128_f8f6f4 v[96:99], v[8:15], v[214:221], v[96:99], v189, v189 op_sel_hi:[0,0,0]
	global_load_lds_dwordx4 v[250:251], off
	s_setprio 0
	s_setprio 1
	s_nop 1
	v_mfma_scale_f32_16x16x128_f8f6f4 v[60:63], v[16:23], v[190:197], v[60:63], v189, v189 op_sel_hi:[0,0,0]
	s_mov_b32 m0, s100
	s_nop 1
	v_mfma_scale_f32_16x16x128_f8f6f4 v[56:59], v[24:31], v[190:197], v[56:59], v189, v189 op_sel_hi:[0,0,0]
	global_load_lds_dwordx4 v[252:253], off
	s_nop 1
	v_mfma_scale_f32_16x16x128_f8f6f4 v[52:55], v[16:23], v[198:205], v[52:55], v189, v189 op_sel_hi:[0,0,0]
	s_mov_b32 m0, s101
	s_nop 1
	v_mfma_scale_f32_16x16x128_f8f6f4 v[48:51], v[24:31], v[198:205], v[48:51], v189, v189 op_sel_hi:[0,0,0]
	global_load_lds_dwordx4 v[174:175], off
	s_nop 1
	v_mfma_scale_f32_16x16x128_f8f6f4 v[44:47], v[16:23], v[206:213], v[44:47], v189, v189 op_sel_hi:[0,0,0]
	s_nop 1
	v_mfma_scale_f32_16x16x128_f8f6f4 v[40:43], v[24:31], v[206:213], v[40:43], v189, v189 op_sel_hi:[0,0,0]
	s_nop 1
	v_mfma_scale_f32_16x16x128_f8f6f4 v[36:39], v[16:23], v[214:221], v[36:39], v189, v189 op_sel_hi:[0,0,0]
	s_nop 1
	v_mfma_scale_f32_16x16x128_f8f6f4 v[32:35], v[24:31], v[214:221], v[32:35], v189, v189 op_sel_hi:[0,0,0]
	s_setprio 0
	s_barrier
	s_add_i32 s71, s71, 2
	s_add_u32 s62, s62, 0x100
	s_addc_u32 s63, s63, 0
	s_add_u32 s65, s65, 0x100
	s_addc_u32 s70, s70, 0
	s_cmp_gt_u32 s71, 13
	s_cbranch_scc0 .LBB0_349
	s_and_b64 vcc, exec, s[18:19]
	s_cbranch_vccz .LBB0_352
	s_barrier

.LBB0_656:
	v_add_u32_e32 v1, s69, v177
	ds_read_b128 v[132:135], v1
	ds_read_b128 v[136:139], v1 offset:1024
	ds_read_b128 v[140:143], v1 offset:2048
	ds_read_b128 v[144:147], v1 offset:3072
	v_add_u32_e32 v1, s70, v177
	s_add_u32 s28, s26, s38
	ds_read_b128 v[180:183], v1
	ds_read_b128 v[184:187], v1 offset:1024
	ds_read_b128 v[188:191], v1 offset:2048
	ds_read_b128 v[192:195], v1 offset:3072
	s_addc_u32 s29, s27, s39
	s_add_u32 s28, s28, 0x100
	s_addc_u32 s29, s29, 0
	s_add_u32 s30, s73, s38
	s_addc_u32 s31, s74, s39
	s_cmpk_eq_i32 s38, 0xf00
	s_cselect_b32 s43, s19, s29
	s_cselect_b32 s42, s71, s28
	s_cselect_b32 s41, s17, s31
	s_cselect_b32 s40, s72, s30
	v_lshl_add_u64 v[244:245], v[170:171], 0, s[38:39]
	s_add_i32 s96, s50, 0xc000
	ds_read_b128 v[196:199], v179
	ds_read_b128 v[200:203], v179 offset:1024
	ds_read_b128 v[204:207], v179 offset:2048
	ds_read_b128 v[208:211], v179 offset:3072
	ds_read_b128 v[212:215], v179 offset:4096
	ds_read_b128 v[216:219], v179 offset:5120
	ds_read_b128 v[220:223], v179 offset:6144
	ds_read_b128 v[224:227], v179 offset:7168
	v_lshl_add_u64 v[2:3], v[172:173], 0, s[38:39]
	s_add_i32 s97, s50, 0xe000
	s_waitcnt vmcnt(6)
	s_waitcnt lgkmcnt(0)
	s_barrier
	s_setprio 1
	s_waitcnt lgkmcnt(0)
	v_mfma_f32_16x16x32_bf16 v[128:131], v[132:135], v[196:199], v[128:131]
	v_mfma_f32_16x16x32_bf16 v[124:127], v[140:143], v[196:199], v[124:127]
	s_mov_b32 m0, s96
	v_mfma_f32_16x16x32_bf16 v[112:115], v[132:135], v[204:207], v[112:115]
	global_load_lds_dwordx4 v[244:245], off
	v_mfma_f32_16x16x32_bf16 v[108:111], v[140:143], v[204:207], v[108:111]
	v_mfma_f32_16x16x32_bf16 v[96:99], v[132:135], v[212:215], v[96:99]
	v_mfma_f32_16x16x32_bf16 v[92:95], v[140:143], v[212:215], v[92:95]
	s_mov_b32 m0, s97
	v_mfma_f32_16x16x32_bf16 v[80:83], v[132:135], v[220:223], v[80:83]
	global_load_lds_dwordx4 v[2:3], off
	v_mfma_f32_16x16x32_bf16 v[76:79], v[140:143], v[220:223], v[76:79]
	v_mfma_f32_16x16x32_bf16 v[128:131], v[136:139], v[200:203], v[128:131]
	v_mfma_f32_16x16x32_bf16 v[124:127], v[144:147], v[200:203], v[124:127]
	v_mfma_f32_16x16x32_bf16 v[112:115], v[136:139], v[208:211], v[112:115]
	v_mfma_f32_16x16x32_bf16 v[108:111], v[144:147], v[208:211], v[108:111]
	v_mfma_f32_16x16x32_bf16 v[96:99], v[136:139], v[216:219], v[96:99]
	v_mfma_f32_16x16x32_bf16 v[92:95], v[144:147], v[216:219], v[92:95]
	v_mfma_f32_16x16x32_bf16 v[80:83], v[136:139], v[224:227], v[80:83]
	v_mfma_f32_16x16x32_bf16 v[76:79], v[144:147], v[224:227], v[76:79]
	s_setprio 0
	s_setprio 1
	v_mfma_f32_16x16x32_bf16 v[120:123], v[180:183], v[196:199], v[120:123]
	v_mfma_f32_16x16x32_bf16 v[116:119], v[188:191], v[196:199], v[116:119]
	v_mfma_f32_16x16x32_bf16 v[104:107], v[180:183], v[204:207], v[104:107]
	v_mfma_f32_16x16x32_bf16 v[100:103], v[188:191], v[204:207], v[100:103]
	v_mfma_f32_16x16x32_bf16 v[88:91], v[180:183], v[212:215], v[88:91]
	v_mfma_f32_16x16x32_bf16 v[84:87], v[188:191], v[212:215], v[84:87]
	v_mfma_f32_16x16x32_bf16 v[72:75], v[180:183], v[220:223], v[72:75]
	v_mfma_f32_16x16x32_bf16 v[68:71], v[188:191], v[220:223], v[68:71]
	v_mfma_f32_16x16x32_bf16 v[120:123], v[184:187], v[200:203], v[120:123]
	v_mfma_f32_16x16x32_bf16 v[116:119], v[192:195], v[200:203], v[116:119]
	v_mfma_f32_16x16x32_bf16 v[104:107], v[184:187], v[208:211], v[104:107]
	v_mfma_f32_16x16x32_bf16 v[100:103], v[192:195], v[208:211], v[100:103]
	v_mfma_f32_16x16x32_bf16 v[88:91], v[184:187], v[216:219], v[88:91]
	v_mfma_f32_16x16x32_bf16 v[84:87], v[192:195], v[216:219], v[84:87]
	v_mfma_f32_16x16x32_bf16 v[72:75], v[184:187], v[224:227], v[72:75]
	v_mfma_f32_16x16x32_bf16 v[68:71], v[192:195], v[224:227], v[68:71]
	s_setprio 0
	s_barrier
	s_add_i32 s28, s69, s49
	v_lshl_add_u64 v[174:175], s[40:41], 0, v[150:151]
	s_mov_b32 s96, s28
	ds_read_b128 v[196:199], v179 offset:16384
	ds_read_b128 v[200:203], v179 offset:17408
	ds_read_b128 v[204:207], v179 offset:18432
	ds_read_b128 v[208:211], v179 offset:19456
	ds_read_b128 v[212:215], v179 offset:20480
	ds_read_b128 v[216:219], v179 offset:21504
	ds_read_b128 v[220:223], v179 offset:22528
	ds_read_b128 v[224:227], v179 offset:23552
	s_add_i32 s97, s28, 0x2000
	s_add_u32 s28, s40, 0x80000
	v_lshl_add_u64 v[228:229], s[40:41], 0, v[154:155]
	s_addc_u32 s29, s41, 0
	s_add_i32 s30, s70, s49
	v_lshl_add_u64 v[244:245], s[28:29], 0, v[150:151]
	s_mov_b32 s98, s30
	v_lshl_add_u64 v[230:231], s[42:43], 0, v[148:149]
	v_lshl_add_u64 v[246:247], s[28:29], 0, v[154:155]
	s_add_i32 s99, s30, 0x2000
	v_lshl_add_u64 v[232:233], s[42:43], 0, v[152:153]
	s_mov_b32 s100, s50
	s_mov_b32 s101, s51
	s_waitcnt vmcnt(2)
	s_waitcnt lgkmcnt(0)
	s_barrier
	s_setprio 1
	s_waitcnt lgkmcnt(0)
	v_mfma_f32_16x16x32_bf16 v[64:67], v[132:135], v[196:199], v[64:67]
	v_mfma_f32_16x16x32_bf16 v[60:63], v[140:143], v[196:199], v[60:63]
	s_mov_b32 m0, s96
	v_mfma_f32_16x16x32_bf16 v[48:51], v[132:135], v[204:207], v[48:51]
	global_load_lds_dwordx4 v[174:175], off
	v_mfma_f32_16x16x32_bf16 v[44:47], v[140:143], v[204:207], v[44:47]
	v_mfma_f32_16x16x32_bf16 v[32:35], v[132:135], v[212:215], v[32:35]
	v_mfma_f32_16x16x32_bf16 v[28:31], v[140:143], v[212:215], v[28:31]
	s_mov_b32 m0, s97
	v_mfma_f32_16x16x32_bf16 v[16:19], v[132:135], v[220:223], v[16:19]
	global_load_lds_dwordx4 v[228:229], off
	v_mfma_f32_16x16x32_bf16 v[12:15], v[140:143], v[220:223], v[12:15]
	v_mfma_f32_16x16x32_bf16 v[64:67], v[136:139], v[200:203], v[64:67]
	v_mfma_f32_16x16x32_bf16 v[60:63], v[144:147], v[200:203], v[60:63]
	s_mov_b32 m0, s98
	v_mfma_f32_16x16x32_bf16 v[48:51], v[136:139], v[208:211], v[48:51]
	global_load_lds_dwordx4 v[244:245], off
	v_mfma_f32_16x16x32_bf16 v[44:47], v[144:147], v[208:211], v[44:47]
	v_mfma_f32_16x16x32_bf16 v[32:35], v[136:139], v[216:219], v[32:35]
	v_mfma_f32_16x16x32_bf16 v[28:31], v[144:147], v[216:219], v[28:31]
	s_mov_b32 m0, s99
	v_mfma_f32_16x16x32_bf16 v[16:19], v[136:139], v[224:227], v[16:19]
	global_load_lds_dwordx4 v[246:247], off
	v_mfma_f32_16x16x32_bf16 v[12:15], v[144:147], v[224:227], v[12:15]
	s_setprio 0
	s_setprio 1
	v_mfma_f32_16x16x32_bf16 v[56:59], v[180:183], v[196:199], v[56:59]
	v_mfma_f32_16x16x32_bf16 v[52:55], v[188:191], v[196:199], v[52:55]
	s_mov_b32 m0, s100
	v_mfma_f32_16x16x32_bf16 v[40:43], v[180:183], v[204:207], v[40:43]
	global_load_lds_dwordx4 v[230:231], off
	v_mfma_f32_16x16x32_bf16 v[36:39], v[188:191], v[204:207], v[36:39]
	v_mfma_f32_16x16x32_bf16 v[24:27], v[180:183], v[212:215], v[24:27]
	v_mfma_f32_16x16x32_bf16 v[20:23], v[188:191], v[212:215], v[20:23]
	s_mov_b32 m0, s101
	v_mfma_f32_16x16x32_bf16 v[8:11], v[180:183], v[220:223], v[8:11]
	global_load_lds_dwordx4 v[232:233], off
	v_mfma_f32_16x16x32_bf16 v[2:5], v[188:191], v[220:223], v[4:7]
	v_mfma_f32_16x16x32_bf16 v[56:59], v[184:187], v[200:203], v[56:59]
	v_mfma_f32_16x16x32_bf16 v[52:55], v[192:195], v[200:203], v[52:55]
	v_mfma_f32_16x16x32_bf16 v[40:43], v[184:187], v[208:211], v[40:43]
	v_mfma_f32_16x16x32_bf16 v[36:39], v[192:195], v[208:211], v[36:39]
	v_mfma_f32_16x16x32_bf16 v[24:27], v[184:187], v[216:219], v[24:27]
	v_mfma_f32_16x16x32_bf16 v[20:23], v[192:195], v[216:219], v[20:23]
	v_mfma_f32_16x16x32_bf16 v[8:11], v[184:187], v[224:227], v[8:11]
	v_mfma_f32_16x16x32_bf16 v[2:5], v[192:195], v[224:227], v[2:5]
	s_setprio 0
	s_barrier
	s_add_i32 s30, 0, 0x18000
	v_add_u32_e32 v1, s30, v177
	s_add_i32 s31, 0, 0x1c000
	ds_read_b128 v[132:135], v1
	ds_read_b128 v[136:139], v1 offset:1024
	ds_read_b128 v[140:143], v1 offset:2048
	ds_read_b128 v[144:147], v1 offset:3072
	v_add_u32_e32 v1, s31, v177
	ds_read_b128 v[180:183], v1
	ds_read_b128 v[184:187], v1 offset:1024
	ds_read_b128 v[188:191], v1 offset:2048
	ds_read_b128 v[192:195], v1 offset:3072
	s_add_u32 s28, s42, 0x80000
	s_addc_u32 s29, s43, 0
	s_mov_b32 s96, s62
	v_lshl_add_u64 v[244:245], s[28:29], 0, v[148:149]
	ds_read_b128 v[196:199], v179 offset:32768
	ds_read_b128 v[200:203], v179 offset:33792
	ds_read_b128 v[204:207], v179 offset:34816
	ds_read_b128 v[208:211], v179 offset:35840
	ds_read_b128 v[212:215], v179 offset:36864
	ds_read_b128 v[216:219], v179 offset:37888
	ds_read_b128 v[220:223], v179 offset:38912
	ds_read_b128 v[224:227], v179 offset:39936
	v_lshl_add_u64 v[6:7], s[28:29], 0, v[152:153]
	s_mov_b32 s97, s63
	s_waitcnt vmcnt(6)
	s_waitcnt lgkmcnt(0)
	s_barrier
	s_setprio 1
	s_waitcnt lgkmcnt(0)
	v_mfma_f32_16x16x32_bf16 v[128:131], v[132:135], v[196:199], v[128:131]
	v_mfma_f32_16x16x32_bf16 v[124:127], v[140:143], v[196:199], v[124:127]
	s_mov_b32 m0, s96
	v_mfma_f32_16x16x32_bf16 v[112:115], v[132:135], v[204:207], v[112:115]
	global_load_lds_dwordx4 v[244:245], off
	v_mfma_f32_16x16x32_bf16 v[108:111], v[140:143], v[204:207], v[108:111]
	v_mfma_f32_16x16x32_bf16 v[96:99], v[132:135], v[212:215], v[96:99]
	v_mfma_f32_16x16x32_bf16 v[92:95], v[140:143], v[212:215], v[92:95]
	s_mov_b32 m0, s97
	v_mfma_f32_16x16x32_bf16 v[80:83], v[132:135], v[220:223], v[80:83]
	global_load_lds_dwordx4 v[6:7], off
	v_mfma_f32_16x16x32_bf16 v[76:79], v[140:143], v[220:223], v[76:79]
	v_mfma_f32_16x16x32_bf16 v[128:131], v[136:139], v[200:203], v[128:131]
	v_mfma_f32_16x16x32_bf16 v[124:127], v[144:147], v[200:203], v[124:127]
	v_mfma_f32_16x16x32_bf16 v[112:115], v[136:139], v[208:211], v[112:115]
	v_mfma_f32_16x16x32_bf16 v[108:111], v[144:147], v[208:211], v[108:111]
	v_mfma_f32_16x16x32_bf16 v[96:99], v[136:139], v[216:219], v[96:99]
	v_mfma_f32_16x16x32_bf16 v[92:95], v[144:147], v[216:219], v[92:95]
	v_mfma_f32_16x16x32_bf16 v[80:83], v[136:139], v[224:227], v[80:83]
	v_mfma_f32_16x16x32_bf16 v[76:79], v[144:147], v[224:227], v[76:79]
	s_setprio 0
	s_setprio 1
	v_mfma_f32_16x16x32_bf16 v[120:123], v[180:183], v[196:199], v[120:123]
	v_mfma_f32_16x16x32_bf16 v[116:119], v[188:191], v[196:199], v[116:119]
	v_mfma_f32_16x16x32_bf16 v[104:107], v[180:183], v[204:207], v[104:107]
	v_mfma_f32_16x16x32_bf16 v[100:103], v[188:191], v[204:207], v[100:103]
	v_mfma_f32_16x16x32_bf16 v[88:91], v[180:183], v[212:215], v[88:91]
	v_mfma_f32_16x16x32_bf16 v[84:87], v[188:191], v[212:215], v[84:87]
	v_mfma_f32_16x16x32_bf16 v[72:75], v[180:183], v[220:223], v[72:75]
	v_mfma_f32_16x16x32_bf16 v[68:71], v[188:191], v[220:223], v[68:71]
	v_mfma_f32_16x16x32_bf16 v[120:123], v[184:187], v[200:203], v[120:123]
	v_mfma_f32_16x16x32_bf16 v[116:119], v[192:195], v[200:203], v[116:119]
	v_mfma_f32_16x16x32_bf16 v[104:107], v[184:187], v[208:211], v[104:107]
	v_mfma_f32_16x16x32_bf16 v[100:103], v[192:195], v[208:211], v[100:103]
	v_mfma_f32_16x16x32_bf16 v[88:91], v[184:187], v[216:219], v[88:91]
	v_mfma_f32_16x16x32_bf16 v[84:87], v[192:195], v[216:219], v[84:87]
	v_mfma_f32_16x16x32_bf16 v[72:75], v[184:187], v[224:227], v[72:75]
	v_mfma_f32_16x16x32_bf16 v[68:71], v[192:195], v[224:227], v[68:71]
	s_setprio 0
	s_barrier
	s_add_i32 s28, s30, s49
	v_lshl_add_u64 v[244:245], v[174:175], 0, s[12:13]
	s_mov_b32 s96, s28
	ds_read_b128 v[196:199], v179 offset:49152
	ds_read_b128 v[200:203], v179 offset:50176
	ds_read_b128 v[204:207], v179 offset:51200
	ds_read_b128 v[208:211], v179 offset:52224
	ds_read_b128 v[212:215], v179 offset:53248
	ds_read_b128 v[216:219], v179 offset:54272
	ds_read_b128 v[220:223], v179 offset:55296
	ds_read_b128 v[224:227], v179 offset:56320
	s_add_i32 s97, s28, 0x2000
	s_add_u32 s28, s40, 0x80080
	v_lshl_add_u64 v[246:247], v[228:229], 0, s[12:13]
	s_addc_u32 s29, s41, 0
	s_add_i32 s30, s31, s49
	v_lshl_add_u64 v[248:249], s[28:29], 0, v[150:151]
	s_mov_b32 s98, s30
	v_lshl_add_u64 v[250:251], s[28:29], 0, v[154:155]
	s_add_i32 s99, s30, 0x2000
	v_lshl_add_u64 v[252:253], v[230:231], 0, s[12:13]
	s_mov_b32 s100, s65
	v_lshl_add_u64 v[254:255], v[232:233], 0, s[12:13]
	s_mov_b32 s101, s66
	s_waitcnt vmcnt(2)
	s_waitcnt lgkmcnt(0)
	s_barrier
	s_setprio 1
	s_waitcnt lgkmcnt(0)
	v_mfma_f32_16x16x32_bf16 v[64:67], v[132:135], v[196:199], v[64:67]
	v_mfma_f32_16x16x32_bf16 v[60:63], v[140:143], v[196:199], v[60:63]
	s_mov_b32 m0, s96
	v_mfma_f32_16x16x32_bf16 v[48:51], v[132:135], v[204:207], v[48:51]
	global_load_lds_dwordx4 v[244:245], off
	v_mfma_f32_16x16x32_bf16 v[44:47], v[140:143], v[204:207], v[44:47]
	v_mfma_f32_16x16x32_bf16 v[32:35], v[132:135], v[212:215], v[32:35]
	v_mfma_f32_16x16x32_bf16 v[28:31], v[140:143], v[212:215], v[28:31]
	s_mov_b32 m0, s97
	v_mfma_f32_16x16x32_bf16 v[16:19], v[132:135], v[220:223], v[16:19]
	global_load_lds_dwordx4 v[246:247], off
	v_mfma_f32_16x16x32_bf16 v[12:15], v[140:143], v[220:223], v[12:15]
	v_mfma_f32_16x16x32_bf16 v[64:67], v[136:139], v[200:203], v[64:67]
	v_mfma_f32_16x16x32_bf16 v[60:63], v[144:147], v[200:203], v[60:63]
	s_mov_b32 m0, s98
	v_mfma_f32_16x16x32_bf16 v[48:51], v[136:139], v[208:211], v[48:51]
	global_load_lds_dwordx4 v[248:249], off
	v_mfma_f32_16x16x32_bf16 v[44:47], v[144:147], v[208:211], v[44:47]
	v_mfma_f32_16x16x32_bf16 v[32:35], v[136:139], v[216:219], v[32:35]
	v_mfma_f32_16x16x32_bf16 v[28:31], v[144:147], v[216:219], v[28:31]
	s_mov_b32 m0, s99
	v_mfma_f32_16x16x32_bf16 v[16:19], v[136:139], v[224:227], v[16:19]
	global_load_lds_dwordx4 v[250:251], off
	v_mfma_f32_16x16x32_bf16 v[12:15], v[144:147], v[224:227], v[12:15]
	s_setprio 0
	s_setprio 1
	v_mfma_f32_16x16x32_bf16 v[56:59], v[180:183], v[196:199], v[56:59]
	v_mfma_f32_16x16x32_bf16 v[52:55], v[188:191], v[196:199], v[52:55]
	s_mov_b32 m0, s100
	v_mfma_f32_16x16x32_bf16 v[40:43], v[180:183], v[204:207], v[40:43]
	global_load_lds_dwordx4 v[252:253], off
	v_mfma_f32_16x16x32_bf16 v[36:39], v[188:191], v[204:207], v[36:39]
	v_mfma_f32_16x16x32_bf16 v[24:27], v[180:183], v[212:215], v[24:27]
	v_mfma_f32_16x16x32_bf16 v[20:23], v[188:191], v[212:215], v[20:23]
	s_mov_b32 m0, s101
	v_mfma_f32_16x16x32_bf16 v[6:9], v[180:183], v[220:223], v[8:11]
	global_load_lds_dwordx4 v[254:255], off
	v_mfma_f32_16x16x32_bf16 v[2:5], v[188:191], v[220:223], v[2:5]
	v_mfma_f32_16x16x32_bf16 v[56:59], v[184:187], v[200:203], v[56:59]
	v_mfma_f32_16x16x32_bf16 v[52:55], v[192:195], v[200:203], v[52:55]
	v_mfma_f32_16x16x32_bf16 v[40:43], v[184:187], v[208:211], v[40:43]
	v_mfma_f32_16x16x32_bf16 v[36:39], v[192:195], v[208:211], v[36:39]
	v_mfma_f32_16x16x32_bf16 v[24:27], v[184:187], v[216:219], v[24:27]
	v_mfma_f32_16x16x32_bf16 v[20:23], v[192:195], v[216:219], v[20:23]
	v_mfma_f32_16x16x32_bf16 v[8:11], v[184:187], v[224:227], v[6:9]
	v_mfma_f32_16x16x32_bf16 v[4:7], v[192:195], v[224:227], v[2:5]
	s_setprio 0
	s_barrier
	s_add_i32 s75, s75, 2
	s_add_u32 s38, s38, 0x100
	s_addc_u32 s39, s39, 0
	s_cmp_gt_u32 s75, 29
	s_cbranch_scc1 .LBB0_659

.LBB0_818:
	v_add_u32_e32 v0, s51, v193
	v_add_u32_e32 v12, s58, v193
	s_add_u32 s28, s12, s26
	ds_read_b128 v[16:19], v0
	ds_read_b128 v[20:23], v0 offset:1024
	ds_read_b128 v[24:27], v0 offset:2048
	ds_read_b128 v[28:31], v0 offset:3072
	ds_read_b128 v[0:3], v12
	ds_read_b128 v[4:7], v12 offset:1024
	ds_read_b128 v[8:11], v12 offset:2048
	ds_read_b128 v[12:15], v12 offset:3072
	s_addc_u32 s29, s13, s27
	s_add_u32 s28, s28, 0x100
	s_addc_u32 s29, s29, 0
	s_add_u32 s30, s23, s26
	s_addc_u32 s31, s59, s27
	s_cmpk_eq_i32 s26, 0x700
	s_cselect_b32 s41, s19, s29
	s_cselect_b32 s40, s60, s28
	s_cselect_b32 s39, s17, s31
	s_cselect_b32 s38, s61, s30
	v_lshl_add_u64 v[244:245], v[178:179], 0, s[26:27]
	s_add_i32 s96, s43, 0xc000
	ds_read_b128 v[182:185], v194
	ds_read_b128 v[186:189], v194 offset:1024
	ds_read_b128 v[196:199], v194 offset:2048
	ds_read_b128 v[200:203], v194 offset:3072
	ds_read_b128 v[204:207], v194 offset:4096
	ds_read_b128 v[208:211], v194 offset:5120
	ds_read_b128 v[212:215], v194 offset:6144
	ds_read_b128 v[216:219], v194 offset:7168
	v_lshl_add_u64 v[220:221], v[180:181], 0, s[26:27]
	s_add_i32 s97, s43, 0xe000
	s_waitcnt vmcnt(6)
	s_waitcnt lgkmcnt(0)
	s_barrier
	s_setprio 1
	s_waitcnt lgkmcnt(0)
	s_nop 1
	v_mfma_scale_f32_16x16x128_f8f6f4 v[156:159], v[16:23], v[182:189], v[156:159], v195, v195 op_sel_hi:[0,0,0]
	s_mov_b32 m0, s96
	s_nop 1
	v_mfma_scale_f32_16x16x128_f8f6f4 v[152:155], v[24:31], v[182:189], v[152:155], v195, v195 op_sel_hi:[0,0,0]
	global_load_lds_dwordx4 v[244:245], off
	s_nop 1
	v_mfma_scale_f32_16x16x128_f8f6f4 v[148:151], v[16:23], v[196:203], v[148:151], v195, v195 op_sel_hi:[0,0,0]
	s_mov_b32 m0, s97
	s_nop 1
	v_mfma_scale_f32_16x16x128_f8f6f4 v[144:147], v[24:31], v[196:203], v[144:147], v195, v195 op_sel_hi:[0,0,0]
	global_load_lds_dwordx4 v[220:221], off
	s_nop 1
	v_mfma_scale_f32_16x16x128_f8f6f4 v[140:143], v[16:23], v[204:211], v[140:143], v195, v195 op_sel_hi:[0,0,0]
	s_nop 1
	v_mfma_scale_f32_16x16x128_f8f6f4 v[136:139], v[24:31], v[204:211], v[136:139], v195, v195 op_sel_hi:[0,0,0]
	s_nop 1
	v_mfma_scale_f32_16x16x128_f8f6f4 v[132:135], v[16:23], v[212:219], v[132:135], v195, v195 op_sel_hi:[0,0,0]
	s_nop 1
	v_mfma_scale_f32_16x16x128_f8f6f4 v[128:131], v[24:31], v[212:219], v[128:131], v195, v195 op_sel_hi:[0,0,0]
	s_setprio 0
	s_setprio 1
	s_nop 1
	v_mfma_scale_f32_16x16x128_f8f6f4 v[92:95], v[0:7], v[182:189], v[92:95], v195, v195 op_sel_hi:[0,0,0]
	s_nop 1
	v_mfma_scale_f32_16x16x128_f8f6f4 v[88:91], v[8:15], v[182:189], v[88:91], v195, v195 op_sel_hi:[0,0,0]
	s_nop 1
	v_mfma_scale_f32_16x16x128_f8f6f4 v[84:87], v[0:7], v[196:203], v[84:87], v195, v195 op_sel_hi:[0,0,0]
	s_nop 1
	v_mfma_scale_f32_16x16x128_f8f6f4 v[80:83], v[8:15], v[196:203], v[80:83], v195, v195 op_sel_hi:[0,0,0]
	s_nop 1
	v_mfma_scale_f32_16x16x128_f8f6f4 v[76:79], v[0:7], v[204:211], v[76:79], v195, v195 op_sel_hi:[0,0,0]
	s_nop 1
	v_mfma_scale_f32_16x16x128_f8f6f4 v[72:75], v[8:15], v[204:211], v[72:75], v195, v195 op_sel_hi:[0,0,0]
	s_nop 1
	v_mfma_scale_f32_16x16x128_f8f6f4 v[68:71], v[0:7], v[212:219], v[68:71], v195, v195 op_sel_hi:[0,0,0]
	s_nop 1
	v_mfma_scale_f32_16x16x128_f8f6f4 v[64:67], v[8:15], v[212:219], v[64:67], v195, v195 op_sel_hi:[0,0,0]
	s_setprio 0
	s_barrier
	s_add_i32 s28, s51, s42
	v_lshl_add_u64 v[182:183], s[38:39], 0, v[162:163]
	s_mov_b32 s96, s28
	ds_read_b128 v[196:199], v194 offset:16384
	ds_read_b128 v[200:203], v194 offset:17408
	ds_read_b128 v[204:207], v194 offset:18432
	ds_read_b128 v[208:211], v194 offset:19456
	ds_read_b128 v[212:215], v194 offset:20480
	ds_read_b128 v[216:219], v194 offset:21504
	ds_read_b128 v[220:223], v194 offset:22528
	ds_read_b128 v[224:227], v194 offset:23552
	s_add_i32 s97, s28, 0x2000
	s_add_u32 s28, s38, 0x40000
	v_lshl_add_u64 v[184:185], s[38:39], 0, v[166:167]
	s_addc_u32 s29, s39, 0
	s_add_i32 s30, s58, s42
	v_lshl_add_u64 v[244:245], s[28:29], 0, v[162:163]
	s_mov_b32 s98, s30
	v_lshl_add_u64 v[188:189], s[40:41], 0, v[164:165]
	v_lshl_add_u64 v[246:247], s[28:29], 0, v[166:167]
	s_add_i32 s99, s30, 0x2000
	v_lshl_add_u64 v[186:187], s[40:41], 0, v[160:161]
	s_mov_b32 s100, s43
	s_mov_b32 s101, s44
	s_waitcnt vmcnt(2)
	s_waitcnt lgkmcnt(0)
	s_barrier
	s_setprio 1
	s_waitcnt lgkmcnt(0)
	s_nop 1
	v_mfma_scale_f32_16x16x128_f8f6f4 v[124:127], v[16:23], v[196:203], v[124:127], v195, v195 op_sel_hi:[0,0,0]
	s_mov_b32 m0, s96
	s_nop 1
	v_mfma_scale_f32_16x16x128_f8f6f4 v[120:123], v[24:31], v[196:203], v[120:123], v195, v195 op_sel_hi:[0,0,0]
	global_load_lds_dwordx4 v[182:183], off
	s_nop 1
	v_mfma_scale_f32_16x16x128_f8f6f4 v[116:119], v[16:23], v[204:211], v[116:119], v195, v195 op_sel_hi:[0,0,0]
	s_mov_b32 m0, s97
	s_nop 1
	v_mfma_scale_f32_16x16x128_f8f6f4 v[112:115], v[24:31], v[204:211], v[112:115], v195, v195 op_sel_hi:[0,0,0]
	global_load_lds_dwordx4 v[184:185], off
	s_nop 1
	v_mfma_scale_f32_16x16x128_f8f6f4 v[108:111], v[16:23], v[212:219], v[108:111], v195, v195 op_sel_hi:[0,0,0]
	s_mov_b32 m0, s98
	s_nop 1
	v_mfma_scale_f32_16x16x128_f8f6f4 v[104:107], v[24:31], v[212:219], v[104:107], v195, v195 op_sel_hi:[0,0,0]
	global_load_lds_dwordx4 v[244:245], off
	s_nop 1
	v_mfma_scale_f32_16x16x128_f8f6f4 v[100:103], v[16:23], v[220:227], v[100:103], v195, v195 op_sel_hi:[0,0,0]
	s_mov_b32 m0, s99
	s_nop 1
	v_mfma_scale_f32_16x16x128_f8f6f4 v[96:99], v[24:31], v[220:227], v[96:99], v195, v195 op_sel_hi:[0,0,0]
	global_load_lds_dwordx4 v[246:247], off
	s_setprio 0
	s_setprio 1
	s_nop 1
	v_mfma_scale_f32_16x16x128_f8f6f4 v[60:63], v[0:7], v[196:203], v[60:63], v195, v195 op_sel_hi:[0,0,0]
	s_mov_b32 m0, s100
	s_nop 1
	v_mfma_scale_f32_16x16x128_f8f6f4 v[56:59], v[8:15], v[196:203], v[56:59], v195, v195 op_sel_hi:[0,0,0]
	global_load_lds_dwordx4 v[186:187], off
	s_nop 1
	v_mfma_scale_f32_16x16x128_f8f6f4 v[52:55], v[0:7], v[204:211], v[52:55], v195, v195 op_sel_hi:[0,0,0]
	s_mov_b32 m0, s101
	s_nop 1
	v_mfma_scale_f32_16x16x128_f8f6f4 v[48:51], v[8:15], v[204:211], v[48:51], v195, v195 op_sel_hi:[0,0,0]
	global_load_lds_dwordx4 v[188:189], off
	s_nop 1
	v_mfma_scale_f32_16x16x128_f8f6f4 v[44:47], v[0:7], v[212:219], v[44:47], v195, v195 op_sel_hi:[0,0,0]
	s_nop 1
	v_mfma_scale_f32_16x16x128_f8f6f4 v[40:43], v[8:15], v[212:219], v[40:43], v195, v195 op_sel_hi:[0,0,0]
	s_nop 1
	v_mfma_scale_f32_16x16x128_f8f6f4 v[36:39], v[0:7], v[220:227], v[36:39], v195, v195 op_sel_hi:[0,0,0]
	s_nop 1
	v_mfma_scale_f32_16x16x128_f8f6f4 v[32:35], v[8:15], v[220:227], v[32:35], v195, v195 op_sel_hi:[0,0,0]
	s_setprio 0
	s_barrier
	s_add_i32 s30, 0, 0x18000
	s_add_i32 s31, 0, 0x1c000
	v_add_u32_e32 v12, s30, v193
	v_add_u32_e32 v28, s31, v193
	ds_read_b128 v[0:3], v12
	ds_read_b128 v[4:7], v12 offset:1024
	ds_read_b128 v[8:11], v12 offset:2048
	ds_read_b128 v[12:15], v12 offset:3072
	ds_read_b128 v[16:19], v28
	ds_read_b128 v[20:23], v28 offset:1024
	ds_read_b128 v[24:27], v28 offset:2048
	ds_read_b128 v[28:31], v28 offset:3072
	s_add_u32 s28, s40, 0x40000
	s_addc_u32 s29, s41, 0
	s_mov_b32 s96, s45
	v_lshl_add_u64 v[244:245], s[28:29], 0, v[160:161]
	ds_read_b128 v[196:199], v194 offset:32768
	ds_read_b128 v[200:203], v194 offset:33792
	ds_read_b128 v[204:207], v194 offset:34816
	ds_read_b128 v[208:211], v194 offset:35840
	ds_read_b128 v[212:215], v194 offset:36864
	ds_read_b128 v[216:219], v194 offset:37888
	ds_read_b128 v[220:223], v194 offset:38912
	ds_read_b128 v[224:227], v194 offset:39936
	v_lshl_add_u64 v[228:229], s[28:29], 0, v[164:165]
	s_mov_b32 s97, s46
	s_waitcnt vmcnt(6)
	s_waitcnt lgkmcnt(0)
	s_barrier
	s_setprio 1
	s_waitcnt lgkmcnt(0)
	s_nop 1
	v_mfma_scale_f32_16x16x128_f8f6f4 v[156:159], v[0:7], v[196:203], v[156:159], v195, v195 op_sel_hi:[0,0,0]
	s_mov_b32 m0, s96
	s_nop 1
	v_mfma_scale_f32_16x16x128_f8f6f4 v[152:155], v[8:15], v[196:203], v[152:155], v195, v195 op_sel_hi:[0,0,0]
	global_load_lds_dwordx4 v[244:245], off
	s_nop 1
	v_mfma_scale_f32_16x16x128_f8f6f4 v[148:151], v[0:7], v[204:211], v[148:151], v195, v195 op_sel_hi:[0,0,0]
	s_mov_b32 m0, s97
	s_nop 1
	v_mfma_scale_f32_16x16x128_f8f6f4 v[144:147], v[8:15], v[204:211], v[144:147], v195, v195 op_sel_hi:[0,0,0]
	global_load_lds_dwordx4 v[228:229], off
	s_nop 1
	v_mfma_scale_f32_16x16x128_f8f6f4 v[140:143], v[0:7], v[212:219], v[140:143], v195, v195 op_sel_hi:[0,0,0]
	s_nop 1
	v_mfma_scale_f32_16x16x128_f8f6f4 v[136:139], v[8:15], v[212:219], v[136:139], v195, v195 op_sel_hi:[0,0,0]
	s_nop 1
	v_mfma_scale_f32_16x16x128_f8f6f4 v[132:135], v[0:7], v[220:227], v[132:135], v195, v195 op_sel_hi:[0,0,0]
	s_nop 1
	v_mfma_scale_f32_16x16x128_f8f6f4 v[128:131], v[8:15], v[220:227], v[128:131], v195, v195 op_sel_hi:[0,0,0]
	s_setprio 0
	s_setprio 1
	s_nop 1
	v_mfma_scale_f32_16x16x128_f8f6f4 v[92:95], v[16:23], v[196:203], v[92:95], v195, v195 op_sel_hi:[0,0,0]
	s_nop 1
	v_mfma_scale_f32_16x16x128_f8f6f4 v[88:91], v[24:31], v[196:203], v[88:91], v195, v195 op_sel_hi:[0,0,0]
	s_nop 1
	v_mfma_scale_f32_16x16x128_f8f6f4 v[84:87], v[16:23], v[204:211], v[84:87], v195, v195 op_sel_hi:[0,0,0]
	s_nop 1
	v_mfma_scale_f32_16x16x128_f8f6f4 v[80:83], v[24:31], v[204:211], v[80:83], v195, v195 op_sel_hi:[0,0,0]
	s_nop 1
	v_mfma_scale_f32_16x16x128_f8f6f4 v[76:79], v[16:23], v[212:219], v[76:79], v195, v195 op_sel_hi:[0,0,0]
	s_nop 1
	v_mfma_scale_f32_16x16x128_f8f6f4 v[72:75], v[24:31], v[212:219], v[72:75], v195, v195 op_sel_hi:[0,0,0]
	s_nop 1
	v_mfma_scale_f32_16x16x128_f8f6f4 v[68:71], v[16:23], v[220:227], v[68:71], v195, v195 op_sel_hi:[0,0,0]
	s_nop 1
	v_mfma_scale_f32_16x16x128_f8f6f4 v[64:67], v[24:31], v[220:227], v[64:67], v195, v195 op_sel_hi:[0,0,0]
	s_setprio 0
	s_barrier
	s_add_i32 s28, s30, s42
	v_lshl_add_u64 v[244:245], v[182:183], 0, s[14:15]
	s_mov_b32 s96, s28
	ds_read_b128 v[196:199], v194 offset:49152
	ds_read_b128 v[200:203], v194 offset:50176
	ds_read_b128 v[204:207], v194 offset:51200
	ds_read_b128 v[208:211], v194 offset:52224
	ds_read_b128 v[212:215], v194 offset:53248
	ds_read_b128 v[216:219], v194 offset:54272
	ds_read_b128 v[220:223], v194 offset:55296
	ds_read_b128 v[224:227], v194 offset:56320
	s_add_i32 s97, s28, 0x2000
	s_add_u32 s28, s38, 0x40080
	v_lshl_add_u64 v[246:247], v[184:185], 0, s[14:15]
	s_addc_u32 s29, s39, 0
	s_add_i32 s30, s31, s42
	v_lshl_add_u64 v[248:249], s[28:29], 0, v[162:163]
	s_mov_b32 s98, s30
	v_lshl_add_u64 v[250:251], s[28:29], 0, v[166:167]
	s_add_i32 s99, s30, 0x2000
	v_lshl_add_u64 v[252:253], v[186:187], 0, s[14:15]
	s_mov_b32 s100, s49
	v_lshl_add_u64 v[182:183], v[188:189], 0, s[14:15]
	s_mov_b32 s101, s50
	s_waitcnt vmcnt(2)
	s_waitcnt lgkmcnt(0)
	s_barrier
	s_setprio 1
	s_waitcnt lgkmcnt(0)
	s_nop 1
	v_mfma_scale_f32_16x16x128_f8f6f4 v[124:127], v[0:7], v[196:203], v[124:127], v195, v195 op_sel_hi:[0,0,0]
	s_mov_b32 m0, s96
	s_nop 1
	v_mfma_scale_f32_16x16x128_f8f6f4 v[120:123], v[8:15], v[196:203], v[120:123], v195, v195 op_sel_hi:[0,0,0]
	global_load_lds_dwordx4 v[244:245], off
	s_nop 1
	v_mfma_scale_f32_16x16x128_f8f6f4 v[116:119], v[0:7], v[204:211], v[116:119], v195, v195 op_sel_hi:[0,0,0]
	s_mov_b32 m0, s97
	s_nop 1
	v_mfma_scale_f32_16x16x128_f8f6f4 v[112:115], v[8:15], v[204:211], v[112:115], v195, v195 op_sel_hi:[0,0,0]
	global_load_lds_dwordx4 v[246:247], off
	s_nop 1
	v_mfma_scale_f32_16x16x128_f8f6f4 v[108:111], v[0:7], v[212:219], v[108:111], v195, v195 op_sel_hi:[0,0,0]
	s_mov_b32 m0, s98
	s_nop 1
	v_mfma_scale_f32_16x16x128_f8f6f4 v[104:107], v[8:15], v[212:219], v[104:107], v195, v195 op_sel_hi:[0,0,0]
	global_load_lds_dwordx4 v[248:249], off
	s_nop 1
	v_mfma_scale_f32_16x16x128_f8f6f4 v[100:103], v[0:7], v[220:227], v[100:103], v195, v195 op_sel_hi:[0,0,0]
	s_mov_b32 m0, s99
	s_nop 1
	v_mfma_scale_f32_16x16x128_f8f6f4 v[96:99], v[8:15], v[220:227], v[96:99], v195, v195 op_sel_hi:[0,0,0]
	global_load_lds_dwordx4 v[250:251], off
	s_setprio 0
	s_setprio 1
	s_nop 1
	v_mfma_scale_f32_16x16x128_f8f6f4 v[60:63], v[16:23], v[196:203], v[60:63], v195, v195 op_sel_hi:[0,0,0]
	s_mov_b32 m0, s100
	s_nop 1
	v_mfma_scale_f32_16x16x128_f8f6f4 v[56:59], v[24:31], v[196:203], v[56:59], v195, v195 op_sel_hi:[0,0,0]
	global_load_lds_dwordx4 v[252:253], off
	s_nop 1
	v_mfma_scale_f32_16x16x128_f8f6f4 v[52:55], v[16:23], v[204:211], v[52:55], v195, v195 op_sel_hi:[0,0,0]
	s_mov_b32 m0, s101
	s_nop 1
	v_mfma_scale_f32_16x16x128_f8f6f4 v[48:51], v[24:31], v[204:211], v[48:51], v195, v195 op_sel_hi:[0,0,0]
	global_load_lds_dwordx4 v[182:183], off
	s_nop 1
	v_mfma_scale_f32_16x16x128_f8f6f4 v[44:47], v[16:23], v[212:219], v[44:47], v195, v195 op_sel_hi:[0,0,0]
	s_nop 1
	v_mfma_scale_f32_16x16x128_f8f6f4 v[40:43], v[24:31], v[212:219], v[40:43], v195, v195 op_sel_hi:[0,0,0]
	s_nop 1
	v_mfma_scale_f32_16x16x128_f8f6f4 v[36:39], v[16:23], v[220:227], v[36:39], v195, v195 op_sel_hi:[0,0,0]
	s_nop 1
	v_mfma_scale_f32_16x16x128_f8f6f4 v[32:35], v[24:31], v[220:227], v[32:35], v195, v195 op_sel_hi:[0,0,0]
	s_setprio 0
	s_barrier
	s_add_i32 s62, s62, 2
	s_add_u32 s26, s26, 0x100
	s_addc_u32 s27, s27, 0
	s_cmp_gt_u32 s62, 13
	s_cbranch_scc0 .LBB0_818
	s_add_u32 s26, s23, 0xffffff00
	s_addc_u32 s27, s59, -1
	s_andn2_b64 vcc, exec, s[4:5]
	s_cbranch_vccnz .LBB0_809
	v_mov_b32_e32 v32, 0
	s_mov_b32 s6, s16
	s_mov_b32 s10, s18
	s_mov_b64 s[12:13], s[24:25]
	s_mov_b32 s48, s22
	v_mov_b32_e32 v33, v32
	v_mov_b32_e32 v34, v32
	v_mov_b32_e32 v35, v32
	v_mov_b32_e32 v36, v32
	v_mov_b32_e32 v37, v32
	v_mov_b32_e32 v38, v32
	v_mov_b32_e32 v39, v32
	v_mov_b32_e32 v40, v32
	v_mov_b32_e32 v41, v32
	v_mov_b32_e32 v42, v32
	v_mov_b32_e32 v43, v32
	v_mov_b32_e32 v44, v32
	v_mov_b32_e32 v45, v32
	v_mov_b32_e32 v46, v32
	v_mov_b32_e32 v47, v32
	v_mov_b32_e32 v48, v32
	v_mov_b32_e32 v49, v32
	v_mov_b32_e32 v50, v32
	v_mov_b32_e32 v51, v32
	v_mov_b32_e32 v52, v32
	v_mov_b32_e32 v53, v32
	v_mov_b32_e32 v54, v32
	v_mov_b32_e32 v55, v32
	v_mov_b32_e32 v56, v32
	v_mov_b32_e32 v57, v32
	v_mov_b32_e32 v58, v32
	v_mov_b32_e32 v59, v32
	v_mov_b32_e32 v60, v32
	v_mov_b32_e32 v61, v32
	v_mov_b32_e32 v62, v32
	v_mov_b32_e32 v63, v32
	v_mov_b32_e32 v96, v32
	v_mov_b32_e32 v97, v32
	v_mov_b32_e32 v98, v32
	v_mov_b32_e32 v99, v32
	v_mov_b32_e32 v100, v32
	v_mov_b32_e32 v101, v32
	v_mov_b32_e32 v102, v32
	v_mov_b32_e32 v103, v32
	v_mov_b32_e32 v104, v32
	v_mov_b32_e32 v105, v32
	v_mov_b32_e32 v106, v32
	v_mov_b32_e32 v107, v32
	v_mov_b32_e32 v108, v32
	v_mov_b32_e32 v109, v32
	v_mov_b32_e32 v110, v32
	v_mov_b32_e32 v111, v32
	v_mov_b32_e32 v112, v32
	v_mov_b32_e32 v113, v32
	v_mov_b32_e32 v114, v32
	v_mov_b32_e32 v115, v32
	v_mov_b32_e32 v116, v32
	v_mov_b32_e32 v117, v32
	v_mov_b32_e32 v118, v32
	v_mov_b32_e32 v119, v32
	v_mov_b32_e32 v120, v32
	v_mov_b32_e32 v121, v32
	v_mov_b32_e32 v122, v32
	v_mov_b32_e32 v123, v32
	v_mov_b32_e32 v124, v32
	v_mov_b32_e32 v125, v32
	v_mov_b32_e32 v126, v32
	v_mov_b32_e32 v127, v32
	v_mov_b32_e32 v64, v32
	v_mov_b32_e32 v65, v32
	v_mov_b32_e32 v66, v32
	v_mov_b32_e32 v67, v32
	v_mov_b32_e32 v68, v32
	v_mov_b32_e32 v69, v32
	v_mov_b32_e32 v70, v32
	v_mov_b32_e32 v71, v32
	v_mov_b32_e32 v72, v32
	v_mov_b32_e32 v73, v32
	v_mov_b32_e32 v74, v32
	v_mov_b32_e32 v75, v32
	v_mov_b32_e32 v76, v32
	v_mov_b32_e32 v77, v32
	v_mov_b32_e32 v78, v32
	v_mov_b32_e32 v79, v32
	v_mov_b32_e32 v80, v32
	v_mov_b32_e32 v81, v32
	v_mov_b32_e32 v82, v32
	v_mov_b32_e32 v83, v32
	v_mov_b32_e32 v84, v32
	v_mov_b32_e32 v85, v32
	v_mov_b32_e32 v86, v32
	v_mov_b32_e32 v87, v32
	v_mov_b32_e32 v88, v32
	v_mov_b32_e32 v89, v32
	v_mov_b32_e32 v90, v32
	v_mov_b32_e32 v91, v32
	v_mov_b32_e32 v92, v32
	v_mov_b32_e32 v93, v32
	v_mov_b32_e32 v94, v32
	v_mov_b32_e32 v95, v32
	v_mov_b32_e32 v128, v32
	v_mov_b32_e32 v129, v32
	v_mov_b32_e32 v130, v32
	v_mov_b32_e32 v131, v32
	v_mov_b32_e32 v132, v32
	v_mov_b32_e32 v133, v32
	v_mov_b32_e32 v134, v32
	v_mov_b32_e32 v135, v32
	v_mov_b32_e32 v136, v32
	v_mov_b32_e32 v137, v32
	v_mov_b32_e32 v138, v32
	v_mov_b32_e32 v139, v32
	v_mov_b32_e32 v140, v32
	v_mov_b32_e32 v141, v32
	v_mov_b32_e32 v142, v32
	v_mov_b32_e32 v143, v32
	v_mov_b32_e32 v144, v32
	v_mov_b32_e32 v145, v32
	v_mov_b32_e32 v146, v32
	v_mov_b32_e32 v147, v32
	v_mov_b32_e32 v148, v32
	v_mov_b32_e32 v149, v32
	v_mov_b32_e32 v150, v32
	v_mov_b32_e32 v151, v32
	v_mov_b32_e32 v152, v32
	v_mov_b32_e32 v153, v32
	v_mov_b32_e32 v154, v32
	v_mov_b32_e32 v155, v32
	v_mov_b32_e32 v156, v32
	v_mov_b32_e32 v157, v32
	v_mov_b32_e32 v158, v32
	v_mov_b32_e32 v159, v32
	s_andn2_b64 vcc, exec, s[0:1]
	s_cbranch_vccnz .LBB0_810

	.amdhsa_kernel _Z14fwd_megakernel4Args
		.amdhsa_group_segment_fixed_size 0
		.amdhsa_private_segment_fixed_size 0
		.amdhsa_kernarg_size 384
		.amdhsa_user_sgpr_count 2
		.amdhsa_user_sgpr_dispatch_ptr 0
		.amdhsa_user_sgpr_queue_ptr 0
		.amdhsa_user_sgpr_kernarg_segment_ptr 1
		.amdhsa_user_sgpr_dispatch_id 0
		.amdhsa_user_sgpr_kernarg_preload_length 0
		.amdhsa_user_sgpr_kernarg_preload_offset 0
		.amdhsa_user_sgpr_private_segment_size 0
		.amdhsa_uses_dynamic_stack 0
		.amdhsa_enable_private_segment 0
		.amdhsa_system_sgpr_workgroup_id_x 1
		.amdhsa_system_sgpr_workgroup_id_y 0
		.amdhsa_system_sgpr_workgroup_id_z 0
		.amdhsa_system_sgpr_workgroup_info 0
		.amdhsa_system_vgpr_workitem_id 2
		.amdhsa_next_free_vgpr 256
		.amdhsa_next_free_sgpr 102
		.amdhsa_accum_offset 256
		.amdhsa_reserve_vcc 1
		.amdhsa_float_round_mode_32 0
		.amdhsa_float_round_mode_16_64 0
		.amdhsa_float_denorm_mode_32 3
		.amdhsa_float_denorm_mode_16_64 3
		.amdhsa_dx10_clamp 1
		.amdhsa_ieee_mode 1
		.amdhsa_fp16_overflow 0
		.amdhsa_tg_split 0
		.amdhsa_exception_fp_ieee_invalid_op 0
		.amdhsa_exception_fp_denorm_src 0
		.amdhsa_exception_fp_ieee_div_zero 0
		.amdhsa_exception_fp_ieee_overflow 0
		.amdhsa_exception_fp_ieee_underflow 0
		.amdhsa_exception_fp_ieee_inexact 0
		.amdhsa_exception_int_div_zero 0
	.end_amdhsa_kernel

amdhsa.kernels:
  - .agpr_count:     0
    .args:
      - .offset:         0
        .size:           128
        .value_kind:     by_value
      - .offset:         128
        .size:           4
        .value_kind:     hidden_block_count_x
      - .offset:         132
        .size:           4
        .value_kind:     hidden_block_count_y
      - .offset:         136
        .size:           4
        .value_kind:     hidden_block_count_z
      - .offset:         140
        .size:           2
        .value_kind:     hidden_group_size_x
      - .offset:         142
        .size:           2
        .value_kind:     hidden_group_size_y
      - .offset:         144
        .size:           2
        .value_kind:     hidden_group_size_z
      - .offset:         146
        .size:           2
        .value_kind:     hidden_remainder_x
      - .offset:         148
        .size:           2
        .value_kind:     hidden_remainder_y
      - .offset:         150
        .size:           2
        .value_kind:     hidden_remainder_z
      - .offset:         168
        .size:           8
        .value_kind:     hidden_global_offset_x
      - .offset:         176
        .size:           8
        .value_kind:     hidden_global_offset_y
      - .offset:         184
        .size:           8
        .value_kind:     hidden_global_offset_z
      - .offset:         192
        .size:           2
        .value_kind:     hidden_grid_dims
      - .offset:         216
        .size:           8
        .value_kind:     hidden_multigrid_sync_arg
      - .offset:         248
        .size:           4
        .value_kind:     hidden_dynamic_lds_size
    .group_segment_fixed_size: 0
    .kernarg_segment_align: 8
    .kernarg_segment_size: 384
    .language:       OpenCL C
    .language_version:
      - 2
      - 0
    .max_flat_workgroup_size: 512
    .name:           _Z14fwd_megakernel4Args
    .private_segment_fixed_size: 0
    .sgpr_count:     108
    .sgpr_spill_count: 9
    .symbol:         _Z14fwd_megakernel4Args.kd
    .uniform_work_group_size: 1
    .uses_dynamic_stack: false
    .vgpr_count:     256
    .vgpr_spill_count: 0
    .wavefront_size: 64
